# attention softmax row reductions via v_permlane16/32_swap instead of ds_bpermute; rope tables of row pairs 3 and 4 fetched one row pair ahead
# baseline (speedup 1.0000x reference)
.LBB0_415:
	s_waitcnt vmcnt(0)
	s_and_b64 vcc, exec, s[48:49]
	s_cbranch_vccnz .Lrope_pf3
	v_lshlrev_b64 v[238:239], 6, v[198:199]
	v_lshl_add_u64 v[238:239], s[64:65], 0, v[238:239]
	flat_load_dwordx4 v[158:161], v[238:239]
	flat_load_dwordx4 v[150:153], v[238:239] offset:16
	flat_load_dwordx4 v[154:157], v[238:239] offset:32
	flat_load_dwordx4 v[146:149], v[238:239] offset:48
	v_lshlrev_b64 v[238:239], 6, v[194:195]
	v_lshl_add_u64 v[238:239], s[64:65], 0, v[238:239]
	flat_load_dwordx4 v[142:145], v[238:239]
	flat_load_dwordx4 v[134:137], v[238:239] offset:16
	flat_load_dwordx4 v[138:141], v[238:239] offset:32
	flat_load_dwordx4 v[130:133], v[238:239] offset:48
.Lrope_pf3:
	v_pk_mul_f32 v[96:97], v[96:97], v[208:209] op_sel_hi:[1,0]
	v_pk_mul_f32 v[94:95], v[94:95], v[208:209] op_sel_hi:[1,0]
	v_pk_mul_f32 v[92:93], v[92:93], v[208:209] op_sel_hi:[1,0]
	s_and_b64 vcc, exec, s[42:43]
	v_pk_mul_f32 v[90:91], v[90:91], v[208:209] op_sel_hi:[1,0]
	s_cbranch_vccnz .LBB0_441
	v_and_b32_e32 v193, 64, v226
	v_xor_b32_e32 v177, 16, v226
	v_add_u32_e32 v193, 64, v193
	v_cmp_lt_i32_e32 vcc, v177, v193
	s_nop 1
	v_cndmask_b32_e32 v177, v226, v177, vcc
	v_lshlrev_b32_e32 v177, 2, v177
	v_mov_b32_e32 v213, v94
	v_mov_b32_e32 v211, v90
	s_nop 0
	v_permlane16_swap_b32 v213, v213
	v_permlane16_swap_b32 v211, v211
	v_cmp_lt_i32_e64 s[4:5], 1, v233
	v_cmp_eq_u32_e64 s[6:7], 1, v233
	v_bfrev_b32_e32 v239, 1
	s_nop 0
	v_cndmask_b32_e64 v239, v239, 0, s[6:7]
	v_mul_f32_e32 v212, v94, v126
	v_mul_f32_e32 v213, v122, v213
	v_xor_b32_e32 v213, v239, v213
	v_add_f32_e32 v212, v212, v213
	v_cndmask_b32_e64 v94, v212, v94, s[4:5]
	v_mul_f32_e32 v210, v90, v118
	v_mul_f32_e32 v211, v114, v211
	v_xor_b32_e32 v211, v239, v211
	v_add_f32_e32 v210, v210, v211
	v_cndmask_b32_e64 v90, v210, v90, s[4:5]
	s_waitcnt lgkmcnt(0)
	v_mov_b32_e32 v213, v95
	v_mov_b32_e32 v211, v91
	s_nop 0
	v_permlane16_swap_b32 v213, v213
	v_permlane16_swap_b32 v211, v211
	v_cmp_lt_i32_e64 s[4:5], 1, v233
	v_cmp_eq_u32_e64 s[6:7], 1, v233
	v_bfrev_b32_e32 v239, 1
	s_nop 0
	v_cndmask_b32_e64 v239, v239, 0, s[6:7]
	v_mul_f32_e32 v210, v127, v95
	v_xor_b32_e32 v238, v239, v123
	v_fma_f32 v213, v238, v213, v210
	v_cndmask_b32_e64 v95, v213, v95, s[4:5]
	v_mul_f32_e32 v212, v119, v91
	v_xor_b32_e32 v238, v239, v115
	v_fma_f32 v211, v238, v211, v212
	v_cndmask_b32_e64 v91, v211, v91, s[4:5]
	s_waitcnt lgkmcnt(0)
	v_mov_b32_e32 v213, v96
	v_mov_b32_e32 v211, v92
	s_nop 0
	v_permlane16_swap_b32 v213, v213
	v_permlane16_swap_b32 v211, v211
	v_cmp_lt_i32_e64 s[4:5], 1, v233
	v_cmp_eq_u32_e64 s[6:7], 1, v233
	v_bfrev_b32_e32 v239, 1
	s_nop 0
	v_cndmask_b32_e64 v239, v239, 0, s[6:7]
	v_mul_f32_e32 v213, v124, v213
	v_xor_b32_e32 v213, v239, v213
	v_fma_f32 v212, v128, v96, v213
	v_cndmask_b32_e64 v96, v212, v96, s[4:5]
	v_mul_f32_e32 v211, v116, v211
	v_xor_b32_e32 v211, v239, v211
	v_fma_f32 v210, v120, v92, v211
	v_cndmask_b32_e64 v92, v210, v92, s[4:5]
	s_waitcnt lgkmcnt(0)
	v_mov_b32_e32 v213, v97
	v_mov_b32_e32 v211, v93
	s_nop 0
	v_permlane16_swap_b32 v213, v213
	v_permlane16_swap_b32 v211, v211
	v_cmp_lt_i32_e64 s[4:5], 1, v233
	v_cmp_eq_u32_e64 s[6:7], 1, v233
	v_bfrev_b32_e32 v239, 1
	s_nop 0
	v_cndmask_b32_e64 v239, v239, 0, s[6:7]
	v_mul_f32_e32 v213, v125, v213
	v_xor_b32_e32 v213, v239, v213
	v_fma_f32 v212, v129, v97, v213
	v_cndmask_b32_e64 v97, v212, v97, s[4:5]
	v_mul_f32_e32 v211, v117, v211
	v_xor_b32_e32 v211, v239, v211
	v_fma_f32 v210, v121, v93, v211
	v_cndmask_b32_e64 v93, v210, v93, s[4:5]

.LBB0_521:
	s_waitcnt vmcnt(0)
	s_and_b64 vcc, exec, s[48:49]
	s_cbranch_vccnz .Lrope_pf4
	v_lshlrev_b64 v[238:239], 6, v[190:191]
	v_lshl_add_u64 v[238:239], s[64:65], 0, v[238:239]
	flat_load_dwordx4 v[126:129], v[238:239]
	flat_load_dwordx4 v[118:121], v[238:239] offset:16
	flat_load_dwordx4 v[122:125], v[238:239] offset:32
	flat_load_dwordx4 v[114:117], v[238:239] offset:48
	v_lshlrev_b64 v[238:239], 6, v[174:175]
	v_lshl_add_u64 v[238:239], s[64:65], 0, v[238:239]
	flat_load_dwordx4 v[110:113], v[238:239]
	flat_load_dwordx4 v[102:105], v[238:239] offset:16
	flat_load_dwordx4 v[106:109], v[238:239] offset:32
	flat_load_dwordx4 v[98:101], v[238:239] offset:48
.Lrope_pf4:
	v_pk_mul_f32 v[64:65], v[64:65], v[200:201] op_sel_hi:[1,0]
	v_pk_mul_f32 v[62:63], v[62:63], v[200:201] op_sel_hi:[1,0]
	v_pk_mul_f32 v[60:61], v[60:61], v[200:201] op_sel_hi:[1,0]
	s_and_b64 vcc, exec, s[42:43]
	v_pk_mul_f32 v[58:59], v[58:59], v[200:201] op_sel_hi:[1,0]
	s_cbranch_vccnz .LBB0_547
	v_and_b32_e32 v67, 64, v226
	v_xor_b32_e32 v66, 16, v226
	v_add_u32_e32 v67, 64, v67
	v_cmp_lt_i32_e32 vcc, v66, v67
	s_nop 1
	v_cndmask_b32_e32 v66, v226, v66, vcc
	v_lshlrev_b32_e32 v70, 2, v66
	v_mov_b32_e32 v69, v62
	v_mov_b32_e32 v67, v58
	s_nop 0
	v_permlane16_swap_b32 v69, v69
	v_permlane16_swap_b32 v67, v67
	v_cmp_lt_i32_e64 s[4:5], 1, v233
	v_cmp_eq_u32_e64 s[6:7], 1, v233
	v_bfrev_b32_e32 v239, 1
	s_nop 0
	v_cndmask_b32_e64 v239, v239, 0, s[6:7]
	v_mul_f32_e32 v68, v62, v158
	v_mul_f32_e32 v69, v154, v69
	v_xor_b32_e32 v69, v239, v69
	v_add_f32_e32 v68, v68, v69
	v_cndmask_b32_e64 v62, v68, v62, s[4:5]
	v_mul_f32_e32 v66, v58, v150
	v_mul_f32_e32 v67, v146, v67
	v_xor_b32_e32 v67, v239, v67
	v_add_f32_e32 v66, v66, v67
	v_cndmask_b32_e64 v58, v66, v58, s[4:5]
	s_waitcnt lgkmcnt(0)
	v_mov_b32_e32 v69, v63
	v_mov_b32_e32 v67, v59
	s_nop 0
	v_permlane16_swap_b32 v69, v69
	v_permlane16_swap_b32 v67, v67
	v_cmp_lt_i32_e64 s[4:5], 1, v233
	v_cmp_eq_u32_e64 s[6:7], 1, v233
	v_bfrev_b32_e32 v239, 1
	s_nop 0
	v_cndmask_b32_e64 v239, v239, 0, s[6:7]
	v_mul_f32_e32 v66, v159, v63
	v_xor_b32_e32 v238, v239, v155
	v_fma_f32 v69, v238, v69, v66
	v_cndmask_b32_e64 v63, v69, v63, s[4:5]
	v_mul_f32_e32 v68, v151, v59
	v_xor_b32_e32 v238, v239, v147
	v_fma_f32 v67, v238, v67, v68
	v_cndmask_b32_e64 v59, v67, v59, s[4:5]
	s_waitcnt lgkmcnt(0)
	v_mov_b32_e32 v69, v64
	v_mov_b32_e32 v67, v60
	s_nop 0
	v_permlane16_swap_b32 v69, v69
	v_permlane16_swap_b32 v67, v67
	v_cmp_lt_i32_e64 s[4:5], 1, v233
	v_cmp_eq_u32_e64 s[6:7], 1, v233
	v_bfrev_b32_e32 v239, 1
	s_nop 0
	v_cndmask_b32_e64 v239, v239, 0, s[6:7]
	v_mul_f32_e32 v69, v156, v69
	v_xor_b32_e32 v69, v239, v69
	v_fma_f32 v68, v160, v64, v69
	v_cndmask_b32_e64 v64, v68, v64, s[4:5]
	v_mul_f32_e32 v67, v148, v67
	v_xor_b32_e32 v67, v239, v67
	v_fma_f32 v66, v152, v60, v67
	v_cndmask_b32_e64 v60, v66, v60, s[4:5]
	s_waitcnt lgkmcnt(0)
	v_mov_b32_e32 v69, v65
	v_mov_b32_e32 v67, v61
	s_nop 0
	v_permlane16_swap_b32 v69, v69
	v_permlane16_swap_b32 v67, v67
	v_cmp_lt_i32_e64 s[4:5], 1, v233
	v_cmp_eq_u32_e64 s[6:7], 1, v233
	v_bfrev_b32_e32 v239, 1
	s_nop 0
	v_cndmask_b32_e64 v239, v239, 0, s[6:7]
	v_mul_f32_e32 v69, v157, v69
	v_xor_b32_e32 v69, v239, v69
	v_fma_f32 v68, v161, v65, v69
	v_cndmask_b32_e64 v65, v68, v65, s[4:5]
	v_mul_f32_e32 v67, v149, v67
	v_xor_b32_e32 v67, v239, v67
	v_fma_f32 v66, v153, v61, v67
	v_cndmask_b32_e64 v61, v66, v61, s[4:5]

.LBB0_625:
	s_waitcnt lgkmcnt(0)
	v_pk_mul_f32 v[44:45], v[38:39], s[36:37] op_sel_hi:[1,0]
	v_pk_mul_f32 v[48:49], v[34:35], s[36:37] op_sel_hi:[1,0]
	v_pk_mul_f32 v[50:51], v[36:37], s[36:37] op_sel_hi:[1,0]
	v_cndmask_b32_e64 v38, v38, v44, s[44:45]
	v_cndmask_b32_e64 v39, v39, v45, s[44:45]
	v_cndmask_b32_e64 v44, v36, v50, s[44:45]
	v_cndmask_b32_e64 v36, v34, v48, s[44:45]
	v_cvt_pk_bf16_f32 v34, v38, v39
	v_lshl_add_u64 v[38:39], v[214:215], 1, v[42:43]
	v_add_co_u32_e32 v38, vcc, 0xfffff100, v38
	v_pk_mul_f32 v[46:47], v[40:41], s[36:37] op_sel_hi:[1,0]
	s_nop 0
	v_addc_co_u32_e32 v39, vcc, -1, v39, vcc
	v_cndmask_b32_e64 v37, v37, v51, s[44:45]
	s_and_b64 vcc, exec, s[48:49]
	v_cndmask_b32_e64 v40, v40, v46, s[44:45]
	v_cndmask_b32_e64 v41, v41, v47, s[44:45]
	v_cndmask_b32_e64 v45, v35, v49, s[44:45]
	v_cvt_pk_bf16_f32 v35, v40, v41
	v_cvt_pk_bf16_f32 v36, v36, v45
	v_cvt_pk_bf16_f32 v37, v44, v37
	flat_store_dwordx4 v[38:39], v[34:37] nt
.LBB0_627:
	s_waitcnt vmcnt(0)
	v_pk_mul_f32 v[32:33], v[32:33], v[192:193] op_sel_hi:[1,0]
	v_pk_mul_f32 v[30:31], v[30:31], v[192:193] op_sel_hi:[1,0]
	v_pk_mul_f32 v[28:29], v[28:29], v[192:193] op_sel_hi:[1,0]
	s_and_b64 vcc, exec, s[42:43]
	v_pk_mul_f32 v[26:27], v[26:27], v[192:193] op_sel_hi:[1,0]
	s_cbranch_vccnz .LBB0_653
	v_and_b32_e32 v35, 64, v226
	v_xor_b32_e32 v34, 16, v226
	v_add_u32_e32 v35, 64, v35
	v_cmp_lt_i32_e32 vcc, v34, v35
	s_nop 1
	v_cndmask_b32_e32 v34, v226, v34, vcc
	v_lshlrev_b32_e32 v38, 2, v34
	v_mov_b32_e32 v37, v30
	v_mov_b32_e32 v35, v26
	s_nop 0
	v_permlane16_swap_b32 v37, v37
	v_permlane16_swap_b32 v35, v35
	v_cmp_lt_i32_e64 s[4:5], 1, v233
	v_cmp_eq_u32_e64 s[6:7], 1, v233
	v_bfrev_b32_e32 v239, 1
	s_nop 0
	v_cndmask_b32_e64 v239, v239, 0, s[6:7]
	v_mul_f32_e32 v36, v30, v126
	v_mul_f32_e32 v37, v122, v37
	v_xor_b32_e32 v37, v239, v37
	v_add_f32_e32 v36, v36, v37
	v_cndmask_b32_e64 v30, v36, v30, s[4:5]
	v_mul_f32_e32 v34, v26, v118
	v_mul_f32_e32 v35, v114, v35
	v_xor_b32_e32 v35, v239, v35
	v_add_f32_e32 v34, v34, v35
	v_cndmask_b32_e64 v26, v34, v26, s[4:5]
	s_waitcnt lgkmcnt(0)
	v_mov_b32_e32 v37, v31
	v_mov_b32_e32 v35, v27
	s_nop 0
	v_permlane16_swap_b32 v37, v37
	v_permlane16_swap_b32 v35, v35
	v_cmp_lt_i32_e64 s[4:5], 1, v233
	v_cmp_eq_u32_e64 s[6:7], 1, v233
	v_bfrev_b32_e32 v239, 1
	s_nop 0
	v_cndmask_b32_e64 v239, v239, 0, s[6:7]
	v_mul_f32_e32 v34, v127, v31
	v_xor_b32_e32 v238, v239, v123
	v_fma_f32 v37, v238, v37, v34
	v_cndmask_b32_e64 v31, v37, v31, s[4:5]
	v_mul_f32_e32 v36, v119, v27
	v_xor_b32_e32 v238, v239, v115
	v_fma_f32 v35, v238, v35, v36
	v_cndmask_b32_e64 v27, v35, v27, s[4:5]
	s_waitcnt lgkmcnt(0)
	v_mov_b32_e32 v37, v32
	v_mov_b32_e32 v35, v28
	s_nop 0
	v_permlane16_swap_b32 v37, v37
	v_permlane16_swap_b32 v35, v35
	v_cmp_lt_i32_e64 s[4:5], 1, v233
	v_cmp_eq_u32_e64 s[6:7], 1, v233
	v_bfrev_b32_e32 v239, 1
	s_nop 0
	v_cndmask_b32_e64 v239, v239, 0, s[6:7]
	v_mul_f32_e32 v37, v124, v37
	v_xor_b32_e32 v37, v239, v37
	v_fma_f32 v36, v128, v32, v37
	v_cndmask_b32_e64 v32, v36, v32, s[4:5]
	v_mul_f32_e32 v35, v116, v35
	v_xor_b32_e32 v35, v239, v35
	v_fma_f32 v34, v120, v28, v35
	v_cndmask_b32_e64 v28, v34, v28, s[4:5]
	s_waitcnt lgkmcnt(0)
	v_mov_b32_e32 v37, v33
	v_mov_b32_e32 v35, v29
	s_nop 0
	v_permlane16_swap_b32 v37, v37
	v_permlane16_swap_b32 v35, v35
	v_cmp_lt_i32_e64 s[4:5], 1, v233
	v_cmp_eq_u32_e64 s[6:7], 1, v233
	v_bfrev_b32_e32 v239, 1
	s_nop 0
	v_cndmask_b32_e64 v239, v239, 0, s[6:7]
	v_mul_f32_e32 v37, v125, v37
	v_xor_b32_e32 v37, v239, v37
	v_fma_f32 v36, v129, v33, v37
	v_cndmask_b32_e64 v33, v36, v33, s[4:5]
	v_mul_f32_e32 v35, v117, v35
	v_xor_b32_e32 v35, v239, v35
	v_fma_f32 v34, v121, v29, v35
	v_cndmask_b32_e64 v29, v34, v29, s[4:5]

.Lattn_mask_join:
	v_xor_b32_e32 v52, 16, v226
	v_add_u32_e32 v53, 64, v53
	v_cmp_lt_i32_e32 vcc, v52, v53
	v_sub_u32_e32 v62, 5, v0
	s_lshl_b32 s10, s8, 1
	v_cndmask_b32_e32 v52, v226, v52, vcc
	v_lshlrev_b32_e32 v54, 2, v52
	v_mov_b32_e32 v52, v2
	s_nop 1
	v_permlane16_swap_b32 v52, v52
	s_add_i32 s10, s10, s12
	v_add_u32_e32 v3, v3, v103
	s_waitcnt lgkmcnt(0)
	v_max_f32_e32 v52, v52, v52
	v_max_f32_e32 v2, v2, v52
	v_xor_b32_e32 v52, 32, v226
	v_cmp_lt_i32_e32 vcc, v52, v53
	v_and_b32_e32 v53, 31, v99
	v_lshrrev_b32_e32 v53, v62, v53
	v_cndmask_b32_e32 v52, v226, v52, vcc
	v_lshlrev_b32_e32 v52, 2, v52
	v_mov_b32_e32 v61, v2
	s_nop 1
	v_permlane32_swap_b32 v61, v61
	v_cmp_ne_u32_e32 vcc, 3, v98
	s_waitcnt lgkmcnt(0)
	v_max_f32_e32 v61, v61, v61
	v_max_f32_e32 v2, v2, v61
	v_sub_f32_e32 v62, v72, v2
	v_sub_f32_e32 v72, v74, v2
	v_sub_f32_e32 v74, v88, v2
	v_mul_f32_e32 v74, 0x3fb8aa3b, v74
	v_exp_f32_e32 v88, v74
	v_sub_f32_e32 v74, v89, v2
	v_mul_f32_e32 v74, 0x3fb8aa3b, v74
	v_exp_f32_e32 v89, v74
	v_sub_f32_e32 v74, v90, v2
	v_mul_f32_e32 v74, 0x3fb8aa3b, v74
	v_exp_f32_e32 v90, v74
	v_sub_f32_e32 v74, v91, v2
	v_sub_f32_e32 v56, v56, v2
	v_mul_f32_e32 v74, 0x3fb8aa3b, v74
	v_mul_f32_e32 v56, 0x3fb8aa3b, v56
	v_sub_f32_e32 v57, v57, v2
	v_exp_f32_e32 v91, v74
	v_sub_f32_e32 v74, v84, v2
	v_exp_f32_e32 v56, v56
	v_mul_f32_e32 v57, 0x3fb8aa3b, v57
	v_sub_f32_e32 v58, v58, v2
	v_mul_f32_e32 v74, 0x3fb8aa3b, v74
	v_exp_f32_e32 v57, v57
	v_mul_f32_e32 v58, 0x3fb8aa3b, v58
	v_sub_f32_e32 v59, v59, v2
	v_exp_f32_e32 v84, v74
	v_sub_f32_e32 v74, v85, v2
	v_exp_f32_e32 v58, v58
	v_mul_f32_e32 v59, 0x3fb8aa3b, v59
	v_mul_f32_e32 v74, 0x3fb8aa3b, v74
	v_exp_f32_e32 v59, v59
	v_mul_f32_e32 v62, 0x3fb8aa3b, v62
	v_sub_f32_e32 v63, v73, v2
	v_exp_f32_e32 v85, v74
	v_sub_f32_e32 v74, v86, v2
	v_add_f32_e32 v61, 0, v56
	v_exp_f32_e32 v62, v62
	v_mul_f32_e32 v63, 0x3fb8aa3b, v63
	v_mul_f32_e32 v74, 0x3fb8aa3b, v74
	v_add_f32_e32 v61, v57, v61
	v_exp_f32_e32 v63, v63
	v_mul_f32_e32 v72, 0x3fb8aa3b, v72
	v_sub_f32_e32 v73, v75, v2
	v_exp_f32_e32 v86, v74
	v_sub_f32_e32 v74, v87, v2
	v_add_f32_e32 v61, v58, v61
	v_exp_f32_e32 v72, v72
	v_mul_f32_e32 v73, 0x3fb8aa3b, v73
	v_mul_f32_e32 v74, 0x3fb8aa3b, v74
	v_add_f32_e32 v61, v59, v61
	v_exp_f32_e32 v73, v73
	v_exp_f32_e32 v87, v74
	v_sub_f32_e32 v74, v80, v2
	v_add_f32_e32 v61, v62, v61
	v_mul_f32_e32 v74, 0x3fb8aa3b, v74
	v_add_f32_e32 v61, v63, v61
	v_exp_f32_e32 v97, v74
	v_sub_f32_e32 v74, v81, v2
	v_add_f32_e32 v61, v72, v61
	v_mul_f32_e32 v74, 0x3fb8aa3b, v74
	v_add_f32_e32 v61, v73, v61
	v_exp_f32_e32 v206, v74
	v_sub_f32_e32 v74, v82, v2
	v_add_f32_e32 v61, v88, v61
	v_mul_f32_e32 v74, 0x3fb8aa3b, v74
	v_add_f32_e32 v61, v89, v61
	v_exp_f32_e32 v207, v74
	v_sub_f32_e32 v74, v83, v2
	v_add_f32_e32 v61, v90, v61
	v_mul_f32_e32 v74, 0x3fb8aa3b, v74
	v_add_f32_e32 v61, v91, v61
	v_exp_f32_e32 v208, v74
	v_sub_f32_e32 v74, v76, v2
	v_add_f32_e32 v61, v84, v61
	v_mul_f32_e32 v74, 0x3fb8aa3b, v74
	v_sub_f32_e32 v64, v64, v2
	v_add_f32_e32 v61, v85, v61
	v_exp_f32_e32 v209, v74
	v_sub_f32_e32 v74, v77, v2
	v_mul_f32_e32 v64, 0x3fb8aa3b, v64
	v_add_f32_e32 v61, v86, v61
	v_mul_f32_e32 v74, 0x3fb8aa3b, v74
	v_exp_f32_e32 v213, v64
	v_sub_f32_e32 v64, v65, v2
	v_add_f32_e32 v61, v87, v61
	v_exp_f32_e32 v210, v74
	v_sub_f32_e32 v74, v78, v2
	v_mul_f32_e32 v64, 0x3fb8aa3b, v64
	v_add_f32_e32 v61, v97, v61
	v_mul_f32_e32 v74, 0x3fb8aa3b, v74
	v_exp_f32_e32 v214, v64
	v_sub_f32_e32 v64, v66, v2
	v_add_f32_e32 v61, v206, v61
	v_exp_f32_e32 v211, v74
	v_sub_f32_e32 v74, v79, v2
	v_mul_f32_e32 v64, 0x3fb8aa3b, v64
	v_add_f32_e32 v61, v207, v61
	v_mul_f32_e32 v74, 0x3fb8aa3b, v74
	v_exp_f32_e32 v215, v64
	v_sub_f32_e32 v64, v67, v2
	v_add_f32_e32 v61, v208, v61
	v_exp_f32_e32 v212, v74
	v_mul_f32_e32 v64, 0x3fb8aa3b, v64
	v_add_f32_e32 v61, v209, v61
	v_exp_f32_e32 v216, v64
	v_sub_f32_e32 v64, v68, v2
	v_add_f32_e32 v61, v210, v61
	v_mul_f32_e32 v64, 0x3fb8aa3b, v64
	v_sub_f32_e32 v60, v60, v2
	v_add_f32_e32 v61, v211, v61
	v_exp_f32_e32 v217, v64
	v_sub_f32_e32 v64, v69, v2
	v_mul_f32_e32 v60, 0x3fb8aa3b, v60
	v_add_f32_e32 v61, v212, v61
	v_mul_f32_e32 v64, 0x3fb8aa3b, v64
	v_exp_f32_e32 v221, v60
	v_add_f32_e32 v61, v213, v61
	v_exp_f32_e32 v218, v64
	v_sub_f32_e32 v64, v70, v2
	v_add_f32_e32 v61, v214, v61
	v_mul_f32_e32 v64, 0x3fb8aa3b, v64
	v_add_f32_e32 v61, v215, v61
	v_exp_f32_e32 v219, v64
	v_cvt_pk_bf16_f32 v56, v56, v57
	v_add_f32_e32 v61, v216, v61
	v_add_f32_e32 v61, v217, v61
	v_cvt_pk_bf16_f32 v57, v58, v59
	v_add_f32_e32 v61, v218, v61
	v_lshl_add_u32 v74, v92, 1, s10
	v_and_b32_sdwa v64, v72, v225 dst_sel:DWORD dst_unused:UNUSED_PAD src0_sel:WORD_1 src1_sel:DWORD
	v_add_f32_e32 v76, v219, v61
	v_sub_f32_e32 v61, v71, v2
	v_cvt_pk_bf16_f32 v58, v62, v63
	v_and_b32_sdwa v59, v73, v225 dst_sel:DWORD dst_unused:UNUSED_PAD src0_sel:WORD_1 src1_sel:DWORD
	v_lshl_add_u32 v68, v197, 1, v74
	v_add3_u32 v69, v72, v64, s23
	v_lshl_add_u32 v72, v198, 1, v74
	v_mul_f32_e32 v61, 0x3fb8aa3b, v61
	v_add_u32_e32 v232, 0x9000, v68
	v_add_u32_e32 v233, 0xb000, v68
	v_add3_u32 v59, v73, v59, s23
	v_add_u32_e32 v234, 0xd000, v68
	v_add_u32_e32 v235, 0x9000, v72
	v_exp_f32_e32 v220, v61
	ds_read2_b64 v[60:63], v232 offset1:4
	ds_read2_b64 v[64:67], v233 offset0:32 offset1:36
	v_perm_b32 v59, v59, v69, s22
	ds_read2_b64 v[68:71], v234 offset0:64 offset1:68
	ds_read2_b64 v[72:75], v235 offset1:4
	v_add_f32_e32 v76, v220, v76
	v_add_f32_e32 v236, v221, v76
	v_sub_f32_e32 v76, v201, v2
	s_waitcnt lgkmcnt(0)
	v_mfma_f32_16x16x32_bf16 v[60:63], v[60:63], v[56:59], 0
	v_mul_f32_e32 v76, 0x3fb8aa3b, v76
	v_exp_f32_e32 v201, v76
	ds_read2_b64 v[76:79], v232 offset0:8 offset1:12
	v_mfma_f32_16x16x32_bf16 v[64:67], v[64:67], v[56:59], 0
	v_sub_f32_e32 v200, v200, v2
	ds_read2_b64 v[80:83], v233 offset0:40 offset1:44
	v_sub_f32_e32 v55, v55, v2
	v_mfma_f32_16x16x32_bf16 v[68:71], v[68:71], v[56:59], 0
	v_mul_f32_e32 v55, 0x3fb8aa3b, v55
	v_exp_f32_e32 v55, v55
	s_movk_i32 s10, 0x1000
	v_mfma_f32_16x16x32_bf16 v[56:59], v[72:75], v[56:59], 0
	v_cvt_pk_bf16_f32 v72, v88, v89
	v_cvt_pk_bf16_f32 v73, v90, v91
	v_cvt_pk_bf16_f32 v74, v84, v85
	v_cvt_pk_bf16_f32 v75, v86, v87
	ds_read2_b64 v[84:87], v234 offset0:72 offset1:76
	v_sub_f32_e32 v91, v203, v2
	s_waitcnt lgkmcnt(0)
	v_mfma_f32_16x16x32_bf16 v[60:63], v[76:79], v[72:75], v[60:63]
	v_mul_f32_e32 v76, 0x3fb8aa3b, v200
	v_exp_f32_e32 v88, v76
	ds_read2_b64 v[76:79], v235 offset0:8 offset1:12
	v_mfma_f32_16x16x32_bf16 v[64:67], v[80:83], v[72:75], v[64:67]
	v_add_f32_e32 v80, v201, v236
	v_add_f32_e32 v89, v88, v80
	v_sub_f32_e32 v80, v202, v2
	v_mfma_f32_16x16x32_bf16 v[68:71], v[84:87], v[72:75], v[68:71]
	v_mul_f32_e32 v80, 0x3fb8aa3b, v80
	s_waitcnt lgkmcnt(0)
	v_mfma_f32_16x16x32_bf16 v[56:59], v[76:79], v[72:75], v[56:59]
	ds_read2_b64 v[76:79], v232 offset0:16 offset1:20
	v_cvt_pk_bf16_f32 v72, v97, v206
	v_cvt_pk_bf16_f32 v73, v207, v208
	v_cvt_pk_bf16_f32 v74, v209, v210
	v_cvt_pk_bf16_f32 v75, v211, v212
	v_exp_f32_e32 v90, v80
	ds_read2_b64 v[80:83], v233 offset0:48 offset1:52
	s_waitcnt lgkmcnt(0)
	v_mfma_f32_16x16x32_bf16 v[60:63], v[76:79], v[72:75], v[60:63]
	v_mul_f32_e32 v76, 0x3fb8aa3b, v91
	ds_read2_b64 v[84:87], v234 offset0:80 offset1:84
	v_exp_f32_e32 v91, v76
	ds_read2_b64 v[76:79], v235 offset0:16 offset1:20
	v_mfma_f32_16x16x32_bf16 v[64:67], v[80:83], v[72:75], v[64:67]
	v_sub_f32_e32 v200, v205, v2
	v_add_f32_e32 v80, v90, v89
	v_add_f32_e32 v89, v91, v80
	s_waitcnt lgkmcnt(0)
	v_mfma_f32_16x16x32_bf16 v[68:71], v[84:87], v[72:75], v[68:71]
	v_sub_f32_e32 v80, v204, v2
	v_mfma_f32_16x16x32_bf16 v[56:59], v[76:79], v[72:75], v[56:59]
	ds_read2_b64 v[76:79], v232 offset0:24 offset1:28
	v_cvt_pk_bf16_f32 v72, v213, v214
	v_cvt_pk_bf16_f32 v73, v215, v216
	v_cvt_pk_bf16_f32 v74, v217, v218
	v_cvt_pk_bf16_f32 v75, v219, v220
	v_mul_f32_e32 v80, 0x3fb8aa3b, v80
	ds_read2_b64 v[84:87], v234 offset0:88 offset1:92
	s_waitcnt lgkmcnt(0)
	v_mfma_f32_16x16x32_bf16 v[60:63], v[76:79], v[72:75], v[60:63]
	v_mul_f32_e32 v76, 0x3fb8aa3b, v200
	v_exp_f32_e32 v200, v76
	ds_read2_b64 v[76:79], v235 offset0:24 offset1:28
	v_exp_f32_e32 v97, v80
	ds_read2_b64 v[80:83], v233 offset0:56 offset1:60
	s_waitcnt lgkmcnt(0)
	v_mfma_f32_16x16x32_bf16 v[76:79], v[76:79], v[72:75], v[56:59]
	s_nop 2
	v_mfma_f32_16x16x32_bf16 v[68:71], v[84:87], v[72:75], v[68:71]
	v_cvt_pk_bf16_f32 v84, v221, v201
	v_mfma_f32_16x16x32_bf16 v[80:83], v[80:83], v[72:75], v[64:67]
	v_cvt_pk_bf16_f32 v85, v88, v90
	v_add_f32_e32 v64, v97, v89
	v_add_f32_e32 v64, v200, v64
	v_add_f32_e32 v204, v55, v64
	ds_read2_b64 v[56:59], v232 offset0:32 offset1:36
	ds_read2_b64 v[72:75], v233 offset0:64 offset1:68
	v_cvt_pk_bf16_f32 v86, v91, v97
	v_and_b32_sdwa v65, v200, v225 dst_sel:DWORD dst_unused:UNUSED_PAD src0_sel:WORD_1 src1_sel:DWORD
	v_add3_u32 v65, v200, v65, s23
	ds_read2_b64 v[88:91], v234 offset0:96 offset1:100
	ds_read2_b64 v[200:203], v235 offset0:32 offset1:36
	v_mov_b32_e32 v54, v204
	s_nop 1
	v_permlane16_swap_b32 v54, v54
	v_and_b32_sdwa v64, v55, v225 dst_sel:DWORD dst_unused:UNUSED_PAD src0_sel:WORD_1 src1_sel:DWORD
	v_add3_u32 v55, v55, v64, s23
	v_perm_b32 v87, v55, v65, s22
	v_lshlrev_b32_e32 v55, 4, v99
	v_and_or_b32 v53, v55, s10, v53
	s_waitcnt lgkmcnt(0)
	v_mfma_f32_16x16x32_bf16 v[64:67], v[56:59], v[84:87], v[60:63]
	v_mfma_f32_16x16x32_bf16 v[60:63], v[72:75], v[84:87], v[80:83]
	v_add_f32_e32 v73, v204, v54
	v_mov_b32_e32 v75, v73
	s_nop 1
	v_permlane32_swap_b32 v75, v75
	v_lshl_add_u32 v72, v3, v0, v53
	v_mfma_f32_16x16x32_bf16 v[56:59], v[88:91], v[84:87], v[68:71]
	v_bfe_u32 v74, v99, 5, 3
	v_lshlrev_b32_e32 v0, 7, v74
	s_waitcnt lgkmcnt(0)
	v_add_f32_e32 v3, v73, v75
	v_mfma_f32_16x16x32_bf16 v[52:55], v[200:203], v[84:87], v[76:79]
	v_ashrrev_i32_e32 v73, 31, v72
	v_lshlrev_b32_e32 v70, 1, v92
	s_and_saveexec_b64 s[34:35], vcc
	s_xor_b64 s[46:47], exec, s[34:35]
	s_cbranch_execz .LBB0_1138
	v_ashrrev_i32_e32 v99, 31, v98
	v_lshlrev_b64 v[68:69], 13, v[98:99]
	v_lshl_add_u64 v[68:69], v[68:69], 0, v[72:73]
	v_lshlrev_b64 v[72:73], 10, v[68:69]
	v_lshl_add_u64 v[72:73], s[52:53], 0, v[72:73]
	v_lshl_add_u64 v[72:73], v[72:73], 0, v[0:1]
	v_bfe_u32 v0, v64, 16, 1
	v_add3_u32 v0, v64, v0, s23
	v_bfe_u32 v64, v65, 16, 1
	v_lshrrev_b32_e32 v0, 16, v0
	v_add3_u32 v64, v65, v64, s23
	v_and_or_b32 v64, v64, s15, v0
	v_cvt_pk_bf16_f32 v65, v66, v67
	v_bfe_u32 v0, v60, 16, 1
	v_add3_u32 v0, v60, v0, s23
	v_bfe_u32 v60, v61, 16, 1
	v_lshrrev_b32_e32 v0, 16, v0
	v_add3_u32 v60, v61, v60, s23
	v_and_or_b32 v60, v60, s15, v0
	v_cvt_pk_bf16_f32 v61, v62, v63
	v_bfe_u32 v0, v56, 16, 1
	v_add3_u32 v0, v56, v0, s23
	v_bfe_u32 v56, v57, 16, 1
	v_lshrrev_b32_e32 v0, 16, v0
	v_add3_u32 v56, v57, v56, s23
	v_and_or_b32 v56, v56, s15, v0
	v_cvt_pk_bf16_f32 v57, v58, v59
	v_bfe_u32 v0, v52, 16, 1
	v_add3_u32 v0, v52, v0, s23
	v_bfe_u32 v52, v53, 16, 1
	v_lshrrev_b32_e32 v0, 16, v0
	v_add3_u32 v52, v53, v52, s23
	v_and_or_b32 v52, v52, s15, v0
	v_mov_b32_e32 v71, v1
	v_lshl_add_u64 v[70:71], v[72:73], 0, v[70:71]
	v_cvt_pk_bf16_f32 v53, v54, v55
	global_store_dwordx2 v[70:71], v[64:65], off nt
	global_store_dwordx2 v[70:71], v[60:61], off offset:32 nt
	global_store_dwordx2 v[70:71], v[56:57], off offset:64 nt
	global_store_dwordx2 v[70:71], v[52:53], off offset:96 nt
	s_and_saveexec_b64 s[58:59], s[42:43]
	s_cbranch_execz .LBB0_1136
	v_lshlrev_b64 v[52:53], 6, v[68:69]
	v_lshl_add_u64 v[52:53], s[54:55], 0, v[52:53]
	v_lshlrev_b32_e32 v0, 3, v74
	v_lshl_add_u64 v[52:53], v[52:53], 0, v[0:1]
	global_store_dwordx2 v[52:53], v[2:3], off
